# select key transform rewritten (3-op sign mask, causal zeroing only on the boundary chunk) in the even-row copy only; odd-row copy as before
# speedup vs baseline: 1.0140x; 1.0002x over previous
.LBB0_551:
	v_readlane_b32 s50, v247, 42
	s_waitcnt vmcnt(1)
	s_add_i32 s63, s82, s50
	s_lshr_b32 s98, s63, 8
	s_lshl_b32 s50, s82, 2
	s_add_i32 s52, s50, 0
	s_add_i32 s50, s52, 0x21600
	v_mov_b32_e32 v136, s50
	ds_read_b32 v136, v136
	v_ashrrev_i32_e32 v137, 31, v0
	v_or_b32_e32 v137, v230, v137
	v_xor_b32_e32 v0, v137, v0
	v_ashrrev_i32_e32 v137, 31, v1
	v_or_b32_e32 v137, v230, v137
	v_xor_b32_e32 v1, v137, v1
	v_ashrrev_i32_e32 v137, 31, v2
	v_or_b32_e32 v137, v230, v137
	v_xor_b32_e32 v2, v137, v2
	v_ashrrev_i32_e32 v137, 31, v3
	v_or_b32_e32 v137, v230, v137
	v_xor_b32_e32 v3, v137, v3
	s_cmp_eq_u32 s98, 0
	s_cbranch_scc0 .Ltr_a_n0
	s_sub_i32 s99, s63, 0
	v_cmp_ge_i32_e32 vcc, s99, v208
	s_nop 1
	v_cndmask_b32_e32 v0, 0, v0, vcc
	s_sub_i32 s99, s63, 1
	v_cmp_ge_i32_e32 vcc, s99, v208
	s_nop 1
	v_cndmask_b32_e32 v1, 0, v1, vcc
	s_sub_i32 s99, s63, 2
	v_cmp_ge_i32_e32 vcc, s99, v208
	s_nop 1
	v_cndmask_b32_e32 v2, 0, v2, vcc
	s_sub_i32 s99, s63, 3
	v_cmp_ge_i32_e32 vcc, s99, v208
	s_nop 1
	v_cndmask_b32_e32 v3, 0, v3, vcc
	s_branch .Ltr_a_end
.Ltr_a_n0:
	s_cmp_lt_u32 s98, 1
	s_cbranch_scc1 .Ltr_a_end
	v_ashrrev_i32_e32 v137, 31, v8
	v_or_b32_e32 v137, v230, v137
	v_xor_b32_e32 v8, v137, v8
	v_ashrrev_i32_e32 v137, 31, v9
	v_or_b32_e32 v137, v230, v137
	v_xor_b32_e32 v9, v137, v9
	v_ashrrev_i32_e32 v137, 31, v10
	v_or_b32_e32 v137, v230, v137
	v_xor_b32_e32 v10, v137, v10
	v_ashrrev_i32_e32 v137, 31, v11
	v_or_b32_e32 v137, v230, v137
	v_xor_b32_e32 v11, v137, v11
	s_cmp_eq_u32 s98, 1
	s_cbranch_scc0 .Ltr_a_n1
	s_sub_i32 s99, s63, 256
	v_cmp_ge_i32_e32 vcc, s99, v208
	s_nop 1
	v_cndmask_b32_e32 v8, 0, v8, vcc
	s_sub_i32 s99, s63, 257
	v_cmp_ge_i32_e32 vcc, s99, v208
	s_nop 1
	v_cndmask_b32_e32 v9, 0, v9, vcc
	s_sub_i32 s99, s63, 258
	v_cmp_ge_i32_e32 vcc, s99, v208
	s_nop 1
	v_cndmask_b32_e32 v10, 0, v10, vcc
	s_sub_i32 s99, s63, 259
	v_cmp_ge_i32_e32 vcc, s99, v208
	s_nop 1
	v_cndmask_b32_e32 v11, 0, v11, vcc
	s_branch .Ltr_a_end
.Ltr_a_n1:
	s_cmp_lt_u32 s98, 2
	s_cbranch_scc1 .Ltr_a_end
	v_ashrrev_i32_e32 v137, 31, v4
	v_or_b32_e32 v137, v230, v137
	v_xor_b32_e32 v4, v137, v4
	v_ashrrev_i32_e32 v137, 31, v5
	v_or_b32_e32 v137, v230, v137
	v_xor_b32_e32 v5, v137, v5
	v_ashrrev_i32_e32 v137, 31, v6
	v_or_b32_e32 v137, v230, v137
	v_xor_b32_e32 v6, v137, v6
	v_ashrrev_i32_e32 v137, 31, v7
	v_or_b32_e32 v137, v230, v137
	v_xor_b32_e32 v7, v137, v7
	s_cmp_eq_u32 s98, 2
	s_cbranch_scc0 .Ltr_a_n2
	s_sub_i32 s99, s63, 512
	v_cmp_ge_i32_e32 vcc, s99, v208
	s_nop 1
	v_cndmask_b32_e32 v4, 0, v4, vcc
	s_sub_i32 s99, s63, 513
	v_cmp_ge_i32_e32 vcc, s99, v208
	s_nop 1
	v_cndmask_b32_e32 v5, 0, v5, vcc
	s_sub_i32 s99, s63, 514
	v_cmp_ge_i32_e32 vcc, s99, v208
	s_nop 1
	v_cndmask_b32_e32 v6, 0, v6, vcc
	s_sub_i32 s99, s63, 515
	v_cmp_ge_i32_e32 vcc, s99, v208
	s_nop 1
	v_cndmask_b32_e32 v7, 0, v7, vcc
	s_branch .Ltr_a_end
.Ltr_a_n2:
	s_cmp_lt_u32 s98, 3
	s_cbranch_scc1 .Ltr_a_end
	v_ashrrev_i32_e32 v137, 31, v12
	v_or_b32_e32 v137, v230, v137
	v_xor_b32_e32 v12, v137, v12
	v_ashrrev_i32_e32 v137, 31, v13
	v_or_b32_e32 v137, v230, v137
	v_xor_b32_e32 v13, v137, v13
	v_ashrrev_i32_e32 v137, 31, v14
	v_or_b32_e32 v137, v230, v137
	v_xor_b32_e32 v14, v137, v14
	v_ashrrev_i32_e32 v137, 31, v15
	v_or_b32_e32 v137, v230, v137
	v_xor_b32_e32 v15, v137, v15
	s_cmp_eq_u32 s98, 3
	s_cbranch_scc0 .Ltr_a_n3
	s_sub_i32 s99, s63, 768
	v_cmp_ge_i32_e32 vcc, s99, v208
	s_nop 1
	v_cndmask_b32_e32 v12, 0, v12, vcc
	s_sub_i32 s99, s63, 769
	v_cmp_ge_i32_e32 vcc, s99, v208
	s_nop 1
	v_cndmask_b32_e32 v13, 0, v13, vcc
	s_sub_i32 s99, s63, 770
	v_cmp_ge_i32_e32 vcc, s99, v208
	s_nop 1
	v_cndmask_b32_e32 v14, 0, v14, vcc
	s_sub_i32 s99, s63, 771
	v_cmp_ge_i32_e32 vcc, s99, v208
	s_nop 1
	v_cndmask_b32_e32 v15, 0, v15, vcc
	s_branch .Ltr_a_end
.Ltr_a_n3:
	s_cmp_lt_u32 s98, 4
	s_cbranch_scc1 .Ltr_a_end
	v_ashrrev_i32_e32 v137, 31, v16
	v_or_b32_e32 v137, v230, v137
	v_xor_b32_e32 v16, v137, v16
	v_ashrrev_i32_e32 v137, 31, v17
	v_or_b32_e32 v137, v230, v137
	v_xor_b32_e32 v17, v137, v17
	v_ashrrev_i32_e32 v137, 31, v18
	v_or_b32_e32 v137, v230, v137
	v_xor_b32_e32 v18, v137, v18
	v_ashrrev_i32_e32 v137, 31, v19
	v_or_b32_e32 v137, v230, v137
	v_xor_b32_e32 v19, v137, v19
	s_cmp_eq_u32 s98, 4
	s_cbranch_scc0 .Ltr_a_n4
	s_sub_i32 s99, s63, 1024
	v_cmp_ge_i32_e32 vcc, s99, v208
	s_nop 1
	v_cndmask_b32_e32 v16, 0, v16, vcc
	s_sub_i32 s99, s63, 1025
	v_cmp_ge_i32_e32 vcc, s99, v208
	s_nop 1
	v_cndmask_b32_e32 v17, 0, v17, vcc
	s_sub_i32 s99, s63, 1026
	v_cmp_ge_i32_e32 vcc, s99, v208
	s_nop 1
	v_cndmask_b32_e32 v18, 0, v18, vcc
	s_sub_i32 s99, s63, 1027
	v_cmp_ge_i32_e32 vcc, s99, v208
	s_nop 1
	v_cndmask_b32_e32 v19, 0, v19, vcc
	s_branch .Ltr_a_end
.Ltr_a_n4:
	s_cmp_lt_u32 s98, 5
	s_cbranch_scc1 .Ltr_a_end
	v_ashrrev_i32_e32 v137, 31, v24
	v_or_b32_e32 v137, v230, v137
	v_xor_b32_e32 v24, v137, v24
	v_ashrrev_i32_e32 v137, 31, v25
	v_or_b32_e32 v137, v230, v137
	v_xor_b32_e32 v25, v137, v25
	v_ashrrev_i32_e32 v137, 31, v26
	v_or_b32_e32 v137, v230, v137
	v_xor_b32_e32 v26, v137, v26
	v_ashrrev_i32_e32 v137, 31, v27
	v_or_b32_e32 v137, v230, v137
	v_xor_b32_e32 v27, v137, v27
	s_cmp_eq_u32 s98, 5
	s_cbranch_scc0 .Ltr_a_n5
	s_sub_i32 s99, s63, 1280
	v_cmp_ge_i32_e32 vcc, s99, v208
	s_nop 1
	v_cndmask_b32_e32 v24, 0, v24, vcc
	s_sub_i32 s99, s63, 1281
	v_cmp_ge_i32_e32 vcc, s99, v208
	s_nop 1
	v_cndmask_b32_e32 v25, 0, v25, vcc
	s_sub_i32 s99, s63, 1282
	v_cmp_ge_i32_e32 vcc, s99, v208
	s_nop 1
	v_cndmask_b32_e32 v26, 0, v26, vcc
	s_sub_i32 s99, s63, 1283
	v_cmp_ge_i32_e32 vcc, s99, v208
	s_nop 1
	v_cndmask_b32_e32 v27, 0, v27, vcc
	s_branch .Ltr_a_end
.Ltr_a_n5:
	s_cmp_lt_u32 s98, 6
	s_cbranch_scc1 .Ltr_a_end
	v_ashrrev_i32_e32 v137, 31, v20
	v_or_b32_e32 v137, v230, v137
	v_xor_b32_e32 v20, v137, v20
	v_ashrrev_i32_e32 v137, 31, v21
	v_or_b32_e32 v137, v230, v137
	v_xor_b32_e32 v21, v137, v21
	v_ashrrev_i32_e32 v137, 31, v22
	v_or_b32_e32 v137, v230, v137
	v_xor_b32_e32 v22, v137, v22
	v_ashrrev_i32_e32 v137, 31, v23
	v_or_b32_e32 v137, v230, v137
	v_xor_b32_e32 v23, v137, v23
	s_cmp_eq_u32 s98, 6
	s_cbranch_scc0 .Ltr_a_n6
	s_sub_i32 s99, s63, 1536
	v_cmp_ge_i32_e32 vcc, s99, v208
	s_nop 1
	v_cndmask_b32_e32 v20, 0, v20, vcc
	s_sub_i32 s99, s63, 1537
	v_cmp_ge_i32_e32 vcc, s99, v208
	s_nop 1
	v_cndmask_b32_e32 v21, 0, v21, vcc
	s_sub_i32 s99, s63, 1538
	v_cmp_ge_i32_e32 vcc, s99, v208
	s_nop 1
	v_cndmask_b32_e32 v22, 0, v22, vcc
	s_sub_i32 s99, s63, 1539
	v_cmp_ge_i32_e32 vcc, s99, v208
	s_nop 1
	v_cndmask_b32_e32 v23, 0, v23, vcc
	s_branch .Ltr_a_end
.Ltr_a_n6:
	s_cmp_lt_u32 s98, 7
	s_cbranch_scc1 .Ltr_a_end
	v_ashrrev_i32_e32 v137, 31, v32
	v_or_b32_e32 v137, v230, v137
	v_xor_b32_e32 v32, v137, v32
	v_ashrrev_i32_e32 v137, 31, v33
	v_or_b32_e32 v137, v230, v137
	v_xor_b32_e32 v33, v137, v33
	v_ashrrev_i32_e32 v137, 31, v34
	v_or_b32_e32 v137, v230, v137
	v_xor_b32_e32 v34, v137, v34
	v_ashrrev_i32_e32 v137, 31, v35
	v_or_b32_e32 v137, v230, v137
	v_xor_b32_e32 v35, v137, v35
	s_cmp_eq_u32 s98, 7
	s_cbranch_scc0 .Ltr_a_n7
	s_sub_i32 s99, s63, 1792
	v_cmp_ge_i32_e32 vcc, s99, v208
	s_nop 1
	v_cndmask_b32_e32 v32, 0, v32, vcc
	s_sub_i32 s99, s63, 1793
	v_cmp_ge_i32_e32 vcc, s99, v208
	s_nop 1
	v_cndmask_b32_e32 v33, 0, v33, vcc
	s_sub_i32 s99, s63, 1794
	v_cmp_ge_i32_e32 vcc, s99, v208
	s_nop 1
	v_cndmask_b32_e32 v34, 0, v34, vcc
	s_sub_i32 s99, s63, 1795
	v_cmp_ge_i32_e32 vcc, s99, v208
	s_nop 1
	v_cndmask_b32_e32 v35, 0, v35, vcc
	s_branch .Ltr_a_end
.Ltr_a_n7:
	s_cmp_lt_u32 s98, 8
	s_cbranch_scc1 .Ltr_a_end
	v_ashrrev_i32_e32 v137, 31, v28
	v_or_b32_e32 v137, v230, v137
	v_xor_b32_e32 v28, v137, v28
	v_ashrrev_i32_e32 v137, 31, v29
	v_or_b32_e32 v137, v230, v137
	v_xor_b32_e32 v29, v137, v29
	v_ashrrev_i32_e32 v137, 31, v30
	v_or_b32_e32 v137, v230, v137
	v_xor_b32_e32 v30, v137, v30
	v_ashrrev_i32_e32 v137, 31, v31
	v_or_b32_e32 v137, v230, v137
	v_xor_b32_e32 v31, v137, v31
	s_cmp_eq_u32 s98, 8
	s_cbranch_scc0 .Ltr_a_n8
	s_sub_i32 s99, s63, 2048
	v_cmp_ge_i32_e32 vcc, s99, v208
	s_nop 1
	v_cndmask_b32_e32 v28, 0, v28, vcc
	s_sub_i32 s99, s63, 2049
	v_cmp_ge_i32_e32 vcc, s99, v208
	s_nop 1
	v_cndmask_b32_e32 v29, 0, v29, vcc
	s_sub_i32 s99, s63, 2050
	v_cmp_ge_i32_e32 vcc, s99, v208
	s_nop 1
	v_cndmask_b32_e32 v30, 0, v30, vcc
	s_sub_i32 s99, s63, 2051
	v_cmp_ge_i32_e32 vcc, s99, v208
	s_nop 1
	v_cndmask_b32_e32 v31, 0, v31, vcc
	s_branch .Ltr_a_end
.Ltr_a_n8:
	s_cmp_lt_u32 s98, 9
	s_cbranch_scc1 .Ltr_a_end
	v_ashrrev_i32_e32 v137, 31, v40
	v_or_b32_e32 v137, v230, v137
	v_xor_b32_e32 v40, v137, v40
	v_ashrrev_i32_e32 v137, 31, v41
	v_or_b32_e32 v137, v230, v137
	v_xor_b32_e32 v41, v137, v41
	v_ashrrev_i32_e32 v137, 31, v42
	v_or_b32_e32 v137, v230, v137
	v_xor_b32_e32 v42, v137, v42
	v_ashrrev_i32_e32 v137, 31, v43
	v_or_b32_e32 v137, v230, v137
	v_xor_b32_e32 v43, v137, v43
	s_cmp_eq_u32 s98, 9
	s_cbranch_scc0 .Ltr_a_n9
	s_sub_i32 s99, s63, 2304
	v_cmp_ge_i32_e32 vcc, s99, v208
	s_nop 1
	v_cndmask_b32_e32 v40, 0, v40, vcc
	s_sub_i32 s99, s63, 2305
	v_cmp_ge_i32_e32 vcc, s99, v208
	s_nop 1
	v_cndmask_b32_e32 v41, 0, v41, vcc
	s_sub_i32 s99, s63, 2306
	v_cmp_ge_i32_e32 vcc, s99, v208
	s_nop 1
	v_cndmask_b32_e32 v42, 0, v42, vcc
	s_sub_i32 s99, s63, 2307
	v_cmp_ge_i32_e32 vcc, s99, v208
	s_nop 1
	v_cndmask_b32_e32 v43, 0, v43, vcc
	s_branch .Ltr_a_end
.Ltr_a_n9:
	s_cmp_lt_u32 s98, 10
	s_cbranch_scc1 .Ltr_a_end
	v_ashrrev_i32_e32 v137, 31, v36
	v_or_b32_e32 v137, v230, v137
	v_xor_b32_e32 v36, v137, v36
	v_ashrrev_i32_e32 v137, 31, v37
	v_or_b32_e32 v137, v230, v137
	v_xor_b32_e32 v37, v137, v37
	v_ashrrev_i32_e32 v137, 31, v38
	v_or_b32_e32 v137, v230, v137
	v_xor_b32_e32 v38, v137, v38
	v_ashrrev_i32_e32 v137, 31, v39
	v_or_b32_e32 v137, v230, v137
	v_xor_b32_e32 v39, v137, v39
	s_cmp_eq_u32 s98, 10
	s_cbranch_scc0 .Ltr_a_n10
	s_sub_i32 s99, s63, 2560
	v_cmp_ge_i32_e32 vcc, s99, v208
	s_nop 1
	v_cndmask_b32_e32 v36, 0, v36, vcc
	s_sub_i32 s99, s63, 2561
	v_cmp_ge_i32_e32 vcc, s99, v208
	s_nop 1
	v_cndmask_b32_e32 v37, 0, v37, vcc
	s_sub_i32 s99, s63, 2562
	v_cmp_ge_i32_e32 vcc, s99, v208
	s_nop 1
	v_cndmask_b32_e32 v38, 0, v38, vcc
	s_sub_i32 s99, s63, 2563
	v_cmp_ge_i32_e32 vcc, s99, v208
	s_nop 1
	v_cndmask_b32_e32 v39, 0, v39, vcc
	s_branch .Ltr_a_end
.Ltr_a_n10:
	s_cmp_lt_u32 s98, 11
	s_cbranch_scc1 .Ltr_a_end
	v_ashrrev_i32_e32 v137, 31, v48
	v_or_b32_e32 v137, v230, v137
	v_xor_b32_e32 v48, v137, v48
	v_ashrrev_i32_e32 v137, 31, v49
	v_or_b32_e32 v137, v230, v137
	v_xor_b32_e32 v49, v137, v49
	v_ashrrev_i32_e32 v137, 31, v50
	v_or_b32_e32 v137, v230, v137
	v_xor_b32_e32 v50, v137, v50
	v_ashrrev_i32_e32 v137, 31, v51
	v_or_b32_e32 v137, v230, v137
	v_xor_b32_e32 v51, v137, v51
	s_cmp_eq_u32 s98, 11
	s_cbranch_scc0 .Ltr_a_n11
	s_sub_i32 s99, s63, 2816
	v_cmp_ge_i32_e32 vcc, s99, v208
	s_nop 1
	v_cndmask_b32_e32 v48, 0, v48, vcc
	s_sub_i32 s99, s63, 2817
	v_cmp_ge_i32_e32 vcc, s99, v208
	s_nop 1
	v_cndmask_b32_e32 v49, 0, v49, vcc
	s_sub_i32 s99, s63, 2818
	v_cmp_ge_i32_e32 vcc, s99, v208
	s_nop 1
	v_cndmask_b32_e32 v50, 0, v50, vcc
	s_sub_i32 s99, s63, 2819
	v_cmp_ge_i32_e32 vcc, s99, v208
	s_nop 1
	v_cndmask_b32_e32 v51, 0, v51, vcc
	s_branch .Ltr_a_end
.Ltr_a_n11:
	s_cmp_lt_u32 s98, 12
	s_cbranch_scc1 .Ltr_a_end
	v_ashrrev_i32_e32 v137, 31, v44
	v_or_b32_e32 v137, v230, v137
	v_xor_b32_e32 v44, v137, v44
	v_ashrrev_i32_e32 v137, 31, v45
	v_or_b32_e32 v137, v230, v137
	v_xor_b32_e32 v45, v137, v45
	v_ashrrev_i32_e32 v137, 31, v46
	v_or_b32_e32 v137, v230, v137
	v_xor_b32_e32 v46, v137, v46
	v_ashrrev_i32_e32 v137, 31, v47
	v_or_b32_e32 v137, v230, v137
	v_xor_b32_e32 v47, v137, v47
	s_cmp_eq_u32 s98, 12
	s_cbranch_scc0 .Ltr_a_n12
	s_sub_i32 s99, s63, 3072
	v_cmp_ge_i32_e32 vcc, s99, v208
	s_nop 1
	v_cndmask_b32_e32 v44, 0, v44, vcc
	s_sub_i32 s99, s63, 3073
	v_cmp_ge_i32_e32 vcc, s99, v208
	s_nop 1
	v_cndmask_b32_e32 v45, 0, v45, vcc
	s_sub_i32 s99, s63, 3074
	v_cmp_ge_i32_e32 vcc, s99, v208
	s_nop 1
	v_cndmask_b32_e32 v46, 0, v46, vcc
	s_sub_i32 s99, s63, 3075
	v_cmp_ge_i32_e32 vcc, s99, v208
	s_nop 1
	v_cndmask_b32_e32 v47, 0, v47, vcc
	s_branch .Ltr_a_end
.Ltr_a_n12:
	s_cmp_lt_u32 s98, 13
	s_cbranch_scc1 .Ltr_a_end
	v_ashrrev_i32_e32 v137, 31, v56
	v_or_b32_e32 v137, v230, v137
	v_xor_b32_e32 v56, v137, v56
	v_ashrrev_i32_e32 v137, 31, v57
	v_or_b32_e32 v137, v230, v137
	v_xor_b32_e32 v57, v137, v57
	v_ashrrev_i32_e32 v137, 31, v58
	v_or_b32_e32 v137, v230, v137
	v_xor_b32_e32 v58, v137, v58
	v_ashrrev_i32_e32 v137, 31, v59
	v_or_b32_e32 v137, v230, v137
	v_xor_b32_e32 v59, v137, v59
	s_cmp_eq_u32 s98, 13
	s_cbranch_scc0 .Ltr_a_n13
	s_sub_i32 s99, s63, 3328
	v_cmp_ge_i32_e32 vcc, s99, v208
	s_nop 1
	v_cndmask_b32_e32 v56, 0, v56, vcc
	s_sub_i32 s99, s63, 3329
	v_cmp_ge_i32_e32 vcc, s99, v208
	s_nop 1
	v_cndmask_b32_e32 v57, 0, v57, vcc
	s_sub_i32 s99, s63, 3330
	v_cmp_ge_i32_e32 vcc, s99, v208
	s_nop 1
	v_cndmask_b32_e32 v58, 0, v58, vcc
	s_sub_i32 s99, s63, 3331
	v_cmp_ge_i32_e32 vcc, s99, v208
	s_nop 1
	v_cndmask_b32_e32 v59, 0, v59, vcc
	s_branch .Ltr_a_end
.Ltr_a_n13:
	s_cmp_lt_u32 s98, 14
	s_cbranch_scc1 .Ltr_a_end
	v_ashrrev_i32_e32 v137, 31, v52
	v_or_b32_e32 v137, v230, v137
	v_xor_b32_e32 v52, v137, v52
	v_ashrrev_i32_e32 v137, 31, v53
	v_or_b32_e32 v137, v230, v137
	v_xor_b32_e32 v53, v137, v53
	v_ashrrev_i32_e32 v137, 31, v54
	v_or_b32_e32 v137, v230, v137
	v_xor_b32_e32 v54, v137, v54
	v_ashrrev_i32_e32 v137, 31, v55
	v_or_b32_e32 v137, v230, v137
	v_xor_b32_e32 v55, v137, v55
	s_cmp_eq_u32 s98, 14
	s_cbranch_scc0 .Ltr_a_n14
	s_sub_i32 s99, s63, 3584
	v_cmp_ge_i32_e32 vcc, s99, v208
	s_nop 1
	v_cndmask_b32_e32 v52, 0, v52, vcc
	s_sub_i32 s99, s63, 3585
	v_cmp_ge_i32_e32 vcc, s99, v208
	s_nop 1
	v_cndmask_b32_e32 v53, 0, v53, vcc
	s_sub_i32 s99, s63, 3586
	v_cmp_ge_i32_e32 vcc, s99, v208
	s_nop 1
	v_cndmask_b32_e32 v54, 0, v54, vcc
	s_sub_i32 s99, s63, 3587
	v_cmp_ge_i32_e32 vcc, s99, v208
	s_nop 1
	v_cndmask_b32_e32 v55, 0, v55, vcc
	s_branch .Ltr_a_end
.Ltr_a_n14:
	s_cmp_lt_u32 s98, 15
	s_cbranch_scc1 .Ltr_a_end
	v_ashrrev_i32_e32 v137, 31, v60
	v_or_b32_e32 v137, v230, v137
	v_xor_b32_e32 v60, v137, v60
	v_ashrrev_i32_e32 v137, 31, v61
	v_or_b32_e32 v137, v230, v137
	v_xor_b32_e32 v61, v137, v61
	v_ashrrev_i32_e32 v137, 31, v62
	v_or_b32_e32 v137, v230, v137
	v_xor_b32_e32 v62, v137, v62
	v_ashrrev_i32_e32 v137, 31, v63
	v_or_b32_e32 v137, v230, v137
	v_xor_b32_e32 v63, v137, v63
	s_cmp_eq_u32 s98, 15
	s_cbranch_scc0 .Ltr_a_n15
	s_sub_i32 s99, s63, 3840
	v_cmp_ge_i32_e32 vcc, s99, v208
	s_nop 1
	v_cndmask_b32_e32 v60, 0, v60, vcc
	s_sub_i32 s99, s63, 3841
	v_cmp_ge_i32_e32 vcc, s99, v208
	s_nop 1
	v_cndmask_b32_e32 v61, 0, v61, vcc
	s_sub_i32 s99, s63, 3842
	v_cmp_ge_i32_e32 vcc, s99, v208
	s_nop 1
	v_cndmask_b32_e32 v62, 0, v62, vcc
	s_sub_i32 s99, s63, 3843
	v_cmp_ge_i32_e32 vcc, s99, v208
	s_nop 1
	v_cndmask_b32_e32 v63, 0, v63, vcc
	s_branch .Ltr_a_end
.Ltr_a_n15:
.Ltr_a_end:
	s_waitcnt lgkmcnt(0)
	v_cmp_gt_i32_e32 vcc, 1, v136
	s_cbranch_vccnz .LBB0_556
	s_add_i32 s50, s52, 0x21700
	v_mov_b32_e32 v137, s50
	ds_read_b32 v137, v137
	s_add_i32 s50, s52, 0x21500
	v_mov_b32_e32 v192, s50
	ds_read_b32 v192, v192
	s_waitcnt lgkmcnt(1)
	v_cmp_eq_u32_e32 vcc, v136, v137
	s_cbranch_vccnz .LBB0_557
	s_mov_b32 s83, 1
	v_mov_b32_e32 v137, 0
	s_mov_b32 s50, 24
	s_mov_b64 s[54:55], 0
